# baseline (speedup 1.0000x reference)
.LBB0_742:
	s_or_b64 exec, exec, s[0:1]
	s_waitcnt vmcnt(40)
	v_mul_f32_e32 v35, v44, v40
	s_waitcnt lgkmcnt(0)
	v_mul_f32_e32 v37, 0x3fb8aa3b, v35
	s_mov_b32 s0, 0x3fb8aa3b
	v_fma_f32 v39, v35, s0, -v37
	v_rndne_f32_e32 v40, v37
	v_fmac_f32_e32 v39, 0x32a5705f, v35
	v_sub_f32_e32 v37, v37, v40
	v_add_f32_e32 v37, v37, v39
	v_exp_f32_e32 v37, v37
	v_cvt_i32_f32_e32 v39, v40
	s_mov_b32 s0, 0xc2ce8ed0
	v_cmp_ngt_f32_e32 vcc, s0, v35
	s_mov_b32 s0, 0x42b17218
	v_ldexp_f32 v37, v37, v39
	v_cndmask_b32_e32 v37, 0, v37, vcc
	v_cmp_nlt_f32_e32 vcc, s0, v35
	s_brev_b32 s0, 1
	v_lshlrev_b32_e32 v126, 5, v43
	v_cndmask_b32_e32 v35, v217, v37, vcc
	v_mul_f32_e32 v37, v48, v48
	v_fmamk_f32 v39, v37, 0xb94c1982, v206
	v_fmaak_f32 v39, v37, v39, 0xbe2aaa9d
	v_mul_f32_e32 v39, v37, v39
	v_fmac_f32_e32 v48, v48, v39
	v_fmamk_f32 v39, v37, 0x37d75334, v207
	v_fmaak_f32 v39, v37, v39, 0x3d2aabf7
	v_fmaak_f32 v39, v37, v39, 0xbf000004
	v_fma_f32 v37, v37, v39, 1.0
	v_and_b32_e32 v39, 1, v47
	v_cmp_eq_u32_e32 vcc, 0, v39
	v_lshlrev_b32_e32 v39, 30, v47
	v_mov_b32_e32 v127, v96
	v_cndmask_b32_e64 v37, -v48, v37, vcc
	v_bitop3_b32 v37, v39, v37, s0 bitop3:0x6c
	v_mul_f32_e32 v39, v50, v50
	v_fmamk_f32 v47, v39, 0xb94c1982, v206
	v_fmaak_f32 v47, v39, v47, 0xbe2aaa9d
	v_mul_f32_e32 v47, v39, v47
	v_fmac_f32_e32 v50, v50, v47
	v_fmamk_f32 v47, v39, 0x37d75334, v207
	v_fmaak_f32 v47, v39, v47, 0x3d2aabf7
	v_fmaak_f32 v47, v39, v47, 0xbf000004
	s_movk_i32 s0, 0x1f8
	v_fma_f32 v39, v39, v47, 1.0
	v_and_b32_e32 v47, 1, v49
	v_cmp_class_f32_e64 vcc, v42, s0
	v_cmp_eq_u32_e64 s[0:1], 0, v47
	v_lshlrev_b32_e32 v47, 30, v49
	v_and_b32_e32 v47, 0x80000000, v47
	v_xor_b32_e32 v42, v46, v42
	v_cndmask_b32_e64 v39, v39, v50, s[0:1]
	v_xor_b32_e32 v42, v42, v47
	v_xor_b32_e32 v39, v42, v39
	v_cndmask_b32_e32 v39, v220, v39, vcc
	v_cndmask_b32_e32 v37, v220, v37, vcc
	v_mul_f32_e32 v42, v35, v39
	v_fma_f32 v48, v35, v37, -1.0
	v_mov_b32_e32 v49, v42
	v_mov_b32_e32 v50, v45
	v_pk_mul_f32 v[46:47], v[44:45], v[44:45]
	v_pk_mul_f32 v[50:51], v[50:51], v[48:49] op_sel:[0,1] op_sel_hi:[0,0]
	v_pk_fma_f32 v[52:53], v[44:45], v[48:49], v[50:51]
	v_pk_fma_f32 v[44:45], v[44:45], v[48:49], v[50:51] op_sel_hi:[0,1,1] neg_lo:[0,0,1] neg_hi:[0,0,1]
	v_pk_add_f32 v[46:47], v[46:47], v[46:47] op_sel:[0,1] op_sel_hi:[0,1]
	v_mul_f32_e32 v40, v35, v37
	v_div_scale_f32 v35, s[0:1], v47, v47, v45
	v_rcp_f32_e32 v37, v35
	s_mov_b32 s14, 0
	v_cmp_gt_u32_e64 s[6:7], 16, v41
	v_mov_b32_e32 v43, v42
	v_fma_f32 v39, -v35, v37, 1.0
	v_fmac_f32_e32 v37, v39, v37
	v_div_scale_f32 v39, vcc, v45, v47, v45
	v_mul_f32_e32 v44, v39, v37
	v_fma_f32 v48, -v35, v44, v39
	v_fmac_f32_e32 v44, v48, v37
	v_fma_f32 v35, -v35, v44, v39
	v_div_fmas_f32 v35, v35, v37, v44
	v_div_fixup_f32 v83, v35, v47, v45
	v_div_scale_f32 v35, s[0:1], v46, v46, v52
	v_rcp_f32_e32 v37, v35
	s_movk_i32 s0, 0x2600
	s_mov_b64 s[8:9], 0
	s_waitcnt vmcnt(6)
	v_xor_b32_e32 v97, 0x80000000, v119
	v_fma_f32 v39, -v35, v37, 1.0
	v_fmac_f32_e32 v37, v39, v37
	v_div_scale_f32 v39, vcc, v52, v46, v52
	v_mul_f32_e32 v44, v39, v37
	v_fma_f32 v45, -v35, v44, v39
	v_fmac_f32_e32 v44, v45, v37
	v_fma_f32 v35, -v35, v44, v39
	v_div_fmas_f32 v35, v35, v37, v44
	v_div_fixup_f32 v82, v35, v46, v52
	v_pk_mul_f32 v[64:65], v[82:83], v[12:13] op_sel:[1,0] op_sel_hi:[0,1]
	v_pk_mul_f32 v[60:61], v[82:83], v[12:13]
	v_pk_mul_f32 v[48:49], v[28:29], v[82:83] op_sel:[0,1] op_sel_hi:[1,0]
	v_pk_mul_f32 v[44:45], v[28:29], v[82:83]
	v_pk_mul_f32 v[56:57], v[82:83], v[20:21] op_sel:[1,0] op_sel_hi:[0,1]
	v_pk_mul_f32 v[52:53], v[82:83], v[20:21]
	v_pk_fma_f32 v[12:13], v[82:83], v[8:9], v[60:61] op_sel:[0,1,1] op_sel_hi:[1,0,0] neg_lo:[0,0,1] neg_hi:[0,0,1]
	v_pk_fma_f32 v[60:61], v[82:83], v[8:9], v[60:61] op_sel:[0,1,1] op_sel_hi:[1,0,0]
	v_pk_fma_f32 v[62:63], v[82:83], v[8:9], v[64:65] neg_lo:[0,0,1] neg_hi:[0,0,1]
	v_pk_fma_f32 v[8:9], v[82:83], v[8:9], v[64:65]
	v_pk_mul_f32 v[74:75], v[82:83], v[4:5] op_sel:[1,0] op_sel_hi:[0,1]
	v_pk_mul_f32 v[4:5], v[82:83], v[4:5]
	v_pk_fma_f32 v[28:29], v[24:25], v[82:83], v[44:45] op_sel:[1,0,1] op_sel_hi:[0,1,0] neg_lo:[0,0,1] neg_hi:[0,0,1]
	v_pk_fma_f32 v[44:45], v[24:25], v[82:83], v[44:45] op_sel:[1,0,1] op_sel_hi:[0,1,0]
	v_pk_fma_f32 v[46:47], v[24:25], v[82:83], v[48:49] neg_lo:[0,0,1] neg_hi:[0,0,1]
	v_pk_fma_f32 v[24:25], v[24:25], v[82:83], v[48:49]
	v_pk_fma_f32 v[20:21], v[16:17], v[82:83], v[52:53] op_sel:[1,0,1] op_sel_hi:[0,1,0] neg_lo:[0,0,1] neg_hi:[0,0,1]
	v_pk_fma_f32 v[52:53], v[16:17], v[82:83], v[52:53] op_sel:[1,0,1] op_sel_hi:[0,1,0]
	v_pk_fma_f32 v[54:55], v[16:17], v[82:83], v[56:57] neg_lo:[0,0,1] neg_hi:[0,0,1]
	v_pk_fma_f32 v[16:17], v[16:17], v[82:83], v[56:57]
	v_mov_b32_e32 v8, v15
	v_pk_fma_f32 v[68:69], v[82:83], v[0:1], v[4:5] op_sel:[0,1,1] op_sel_hi:[1,0,0] neg_lo:[0,0,1] neg_hi:[0,0,1]
	v_pk_fma_f32 v[70:71], v[82:83], v[0:1], v[4:5] op_sel:[0,1,1] op_sel_hi:[1,0,0]
	v_pk_fma_f32 v[72:73], v[82:83], v[0:1], v[74:75] neg_lo:[0,0,1] neg_hi:[0,0,1]
	v_pk_fma_f32 v[74:75], v[82:83], v[0:1], v[74:75]
	v_pk_mul_f32 v[0:1], v[82:83], v[6:7] op_sel:[1,0] op_sel_hi:[0,0]
	v_mov_b32_e32 v24, v31
	v_mov_b32_e32 v16, v23
	v_pk_mul_f32 v[66:67], v[82:83], v[14:15] op_sel:[1,0] op_sel_hi:[0,0]
	v_pk_mul_f32 v[14:15], v[82:83], v[8:9] op_sel:[1,0] op_sel_hi:[0,0]
	v_mov_b32_e32 v8, v11
	v_pk_fma_f32 v[76:77], v[82:83], v[2:3], v[0:1] op_sel_hi:[1,0,1] neg_lo:[0,0,1] neg_hi:[0,0,1]
	v_pk_fma_f32 v[78:79], v[82:83], v[2:3], v[0:1] op_sel_hi:[1,0,1]
	v_mov_b32_e32 v0, v7
	v_pk_mul_f32 v[50:51], v[30:31], v[82:83] op_sel:[0,1] op_sel_hi:[0,0]
	v_pk_mul_f32 v[30:31], v[24:25], v[82:83] op_sel:[0,1] op_sel_hi:[0,0]
	v_mov_b32_e32 v24, v27
	v_pk_mul_f32 v[58:59], v[82:83], v[22:23] op_sel:[1,0] op_sel_hi:[0,0]
	v_pk_mul_f32 v[22:23], v[82:83], v[16:17] op_sel:[1,0] op_sel_hi:[0,0]
	v_mov_b32_e32 v16, v19
	v_pk_fma_f32 v[64:65], v[82:83], v[10:11], v[66:67] op_sel_hi:[1,0,1] neg_lo:[0,0,1] neg_hi:[0,0,1]
	v_pk_fma_f32 v[66:67], v[82:83], v[10:11], v[66:67] op_sel_hi:[1,0,1]
	v_pk_fma_f32 v[10:11], v[82:83], v[8:9], v[14:15] op_sel_hi:[1,0,1] neg_lo:[0,0,1] neg_hi:[0,0,1]
	v_pk_fma_f32 v[14:15], v[82:83], v[8:9], v[14:15] op_sel_hi:[1,0,1]
	v_pk_mul_f32 v[0:1], v[82:83], v[0:1] op_sel:[1,0] op_sel_hi:[0,0]
	v_mov_b32_e32 v2, v3
	v_mul_lo_u32 v8, v84, s0
	s_mov_b32 s0, 0x2400000
	v_pk_fma_f32 v[48:49], v[26:27], v[82:83], v[50:51] op_sel_hi:[0,1,1] neg_lo:[0,0,1] neg_hi:[0,0,1]
	v_pk_fma_f32 v[50:51], v[26:27], v[82:83], v[50:51] op_sel_hi:[0,1,1]
	v_pk_fma_f32 v[26:27], v[24:25], v[82:83], v[30:31] op_sel_hi:[0,1,1] neg_lo:[0,0,1] neg_hi:[0,0,1]
	v_pk_fma_f32 v[30:31], v[24:25], v[82:83], v[30:31] op_sel_hi:[0,1,1]
	v_pk_fma_f32 v[56:57], v[18:19], v[82:83], v[58:59] op_sel_hi:[0,1,1] neg_lo:[0,0,1] neg_hi:[0,0,1]
	v_pk_fma_f32 v[58:59], v[18:19], v[82:83], v[58:59] op_sel_hi:[0,1,1]
	v_pk_fma_f32 v[18:19], v[16:17], v[82:83], v[22:23] op_sel_hi:[0,1,1] neg_lo:[0,0,1] neg_hi:[0,0,1]
	v_pk_fma_f32 v[22:23], v[16:17], v[82:83], v[22:23] op_sel_hi:[0,1,1]
	v_pk_fma_f32 v[80:81], v[82:83], v[2:3], v[0:1] op_sel_hi:[1,0,1] neg_lo:[0,0,1] neg_hi:[0,0,1]
	v_pk_fma_f32 v[82:83], v[82:83], v[2:3], v[0:1] op_sel_hi:[1,0,1]
	v_mul_lo_u32 v0, v86, s0
	v_readlane_b32 s0, v253, 27
	v_mov_b32_e32 v1, v96
	v_readlane_b32 s1, v253, 28
	v_cmp_eq_u32_e32 vcc, 0, v86
	v_mov_b64_e32 v[2:3], s[96:97]
	v_lshl_add_u64 v[84:85], s[0:1], 0, v[0:1]
	v_xad_u32 v0, v109, -1, v90
	v_cndmask_b32_e32 v0, v0, v109, vcc
	v_lshl_add_u64 v[0:1], v[32:33], 0, v[0:1]
	v_mad_u64_u32 v[2:3], s[0:1], v0, s43, v[2:3]
	v_mov_b32_e32 v0, v3
	v_mad_u64_u32 v[0:1], s[0:1], v1, s43, v[0:1]
	v_mov_b32_e32 v3, v0
	v_lshl_add_u64 v[4:5], v[2:3], 0, v[126:127]
	global_load_dwordx4 v[0:3], v[4:5], off offset:3088
	s_nop 0
	global_load_dwordx4 v[4:7], v[4:5], off offset:3072
	s_movk_i32 s0, 0x210
	v_mad_u32_u24 v22, v109, s0, v8
	v_lshrrev_b32_e32 v24, 2, v146
	v_lshl_or_b32 v22, v87, 2, v22
	v_and_b32_e32 v24, 12, v24
	v_lshl_add_u64 v[84:85], v[84:85], 0, v[126:127]
	v_lshlrev_b32_e32 v86, 1, v109
	v_mov_b32_e32 v87, v96
	v_lshl_add_u32 v30, v41, 6, v8
	v_mul_i32_i24_e32 v44, 0xffffffc4, v41
	v_sub_u32_e32 v39, v90, v109
	v_mov_b32_e32 v29, v45
	v_mov_b32_e32 v47, v25
	v_mov_b32_e32 v49, v51
	v_mov_b32_e32 v27, v31
	v_mov_b32_e32 v21, v53
	v_mov_b32_e32 v55, v17
	v_mov_b32_e32 v57, v59
	v_mov_b32_e32 v19, v23
	v_mov_b32_e32 v13, v61
	v_mov_b32_e32 v63, v9
	v_mov_b32_e32 v65, v67
	v_mov_b32_e32 v11, v15
	v_mov_b32_e32 v69, v71
	v_mov_b32_e32 v73, v75
	v_mov_b32_e32 v77, v79
	v_mov_b32_e32 v81, v83
	v_lshrrev_b32_e32 v14, 4, v90
	v_lshl_or_b32 v16, v41, 2, v8
	v_lshl_add_u64 v[84:85], v[84:85], 0, v[86:87]
	v_mov_b32_e32 v41, v40
	v_lshl_add_u64 v[86:87], s[96:97], 0, v[126:127]
	v_xad_u32 v35, v24, -1, v90
	v_or_b32_e32 v37, 16, v109
	v_subrev_u32_e32 v39, 17, v39
	v_add_u32_e32 v44, v30, v44
	v_xor_b32_e32 v50, 0x80000000, v110
	v_xor_b32_e32 v52, 0x80000000, v111
	v_xor_b32_e32 v58, 0x80000000, v112
	v_xor_b32_e32 v60, 0x80000000, v113
	v_xor_b32_e32 v66, 0x80000000, v114
	v_xor_b32_e32 v70, 0x80000000, v115
	v_xor_b32_e32 v74, 0x80000000, v116
	v_xor_b32_e32 v78, 0x80000000, v117
	v_xor_b32_e32 v82, 0x80000000, v118
	s_waitcnt vmcnt(7)
	v_xor_b32_e32 v109, 0x80000000, v120
	s_waitcnt vmcnt(6)
	v_xor_b32_e32 v110, 0x80000000, v121
	s_waitcnt vmcnt(5)
	v_xor_b32_e32 v111, 0x80000000, v122
	s_waitcnt vmcnt(4)
	v_xor_b32_e32 v112, 0x80000000, v123
	s_waitcnt vmcnt(3)
	v_xor_b32_e32 v113, 0x80000000, v124
	s_waitcnt vmcnt(2)
	v_xor_b32_e32 v114, 0x80000000, v125
	s_waitcnt vmcnt(0)
	v_mov_b32_e32 v176, v28
	v_mov_b32_e32 v177, v25
	v_mov_b32_e32 v178, v46
	v_mov_b32_e32 v179, v45
	v_mov_b32_e32 v180, v48
	v_mov_b32_e32 v181, v51
	v_mov_b32_e32 v182, v26
	v_mov_b32_e32 v183, v31
	v_mov_b32_e32 v184, v20
	v_mov_b32_e32 v185, v17
	v_mov_b32_e32 v186, v54
	v_mov_b32_e32 v187, v53
	v_mov_b32_e32 v188, v56
	v_mov_b32_e32 v189, v59
	v_mov_b32_e32 v190, v18
	v_mov_b32_e32 v191, v23
	v_mov_b32_e32 v192, v12
	v_mov_b32_e32 v193, v9
	v_mov_b32_e32 v194, v62
	v_mov_b32_e32 v195, v61
	v_mov_b32_e32 v196, v64
	v_mov_b32_e32 v197, v67
	v_mov_b32_e32 v198, v10
	v_mov_b32_e32 v199, v15
	v_mov_b32_e32 v200, v68
	v_mov_b32_e32 v201, v75
	v_mov_b32_e32 v202, v72
	v_mov_b32_e32 v203, v71
	v_mov_b32_e32 v160, v76
	v_mov_b32_e32 v161, v79
	v_mov_b32_e32 v162, v80
	v_mov_b32_e32 v163, v83
	v_mov_b32_e32 v248, v40
	v_mov_b32_e32 v249, v42
	s_mov_b32 s15, 0
	s_branch .LBB0_744

.LBB0_744:
	s_and_saveexec_b64 s[0:1], s[6:7]
	s_cbranch_execz .LBB0_746
	s_waitcnt vmcnt(4)
	v_lshlrev_b32_e32 v116, 16, v4
	v_and_b32_e32 v117, 0xffff0000, v4
	v_lshlrev_b32_e32 v118, 16, v5
	v_and_b32_e32 v119, 0xffff0000, v5
	v_lshlrev_b32_e32 v120, 16, v6
	v_and_b32_e32 v121, 0xffff0000, v6
	v_lshlrev_b32_e32 v122, 16, v7
	v_and_b32_e32 v123, 0xffff0000, v7
	v_lshlrev_b32_e32 v124, 16, v0
	v_and_b32_e32 v125, 0xffff0000, v0
	v_lshlrev_b32_e32 v126, 16, v1
	v_and_b32_e32 v127, 0xffff0000, v1
	v_lshlrev_b32_e32 v128, 16, v2
	v_and_b32_e32 v129, 0xffff0000, v2
	v_lshlrev_b32_e32 v130, 16, v3
	v_and_b32_e32 v131, 0xffff0000, v3
	ds_write_b128 v30, v[116:119]
	ds_write_b128 v30, v[120:123] offset:16
	ds_write_b128 v30, v[124:127] offset:32
	ds_write_b128 v30, v[128:131] offset:48
.LBB0_746:
	s_or_b64 exec, exec, s[0:1]
	s_add_i32 s15, s15, 1
	v_cmp_lt_u32_e64 s[0:1], s15, v14
	s_waitcnt lgkmcnt(0)
	s_barrier
	s_and_saveexec_b64 s[10:11], s[0:1]
	s_cbranch_execz .LBB0_743
	s_waitcnt vmcnt(4)
	v_add_u32_e32 v0, s14, v37
	v_cndmask_b32_e32 v0, v39, v0, vcc
	v_ashrrev_i32_e32 v1, 31, v0
	v_lshl_add_u64 v[0:1], v[32:33], 0, v[0:1]
	s_waitcnt vmcnt(4)
	v_mad_u64_u32 v[4:5], s[0:1], v0, s43, v[86:87]
	v_mov_b32_e32 v0, v5
	v_mad_u64_u32 v[0:1], s[0:1], v1, s43, v[0:1]
	v_mov_b32_e32 v5, v0
	global_load_dwordx4 v[0:3], v[4:5], off offset:3088
	s_nop 0
	global_load_dwordx4 v[4:7], v[4:5], off offset:3072
	s_branch .LBB0_743
